# sparse attention phase: static s_setprio 1 for the second wave half (reset at the phase barrier)
# baseline (speedup 1.0000x reference)
; DI float bflo(unsigned v) { return __uint_as_float(v << 16); }
; DI float bfhi(unsigned v) { return __uint_as_float(v & 0xffff0000u); }
; DI int opaque_tid() { int t = threadIdx.x; asm volatile("" : "+v"(t)); return t; }
; DI void sparse_attn(const Params& p, u16* qabs, const float* ssq, const u16* ckv, const int* sel, char* smem) {
;   constexpr int KS = 544;
;   const int tid = opaque_tid(), lane = tid & 63, w = __builtin_amdgcn_readfirstlane(tid >> 6);
;   const int g = lane >> 4, h = lane & 15, q4 = (lane & 15) >> 2, p4 = lane & 3;
;   char* tl = smem + w * (32 * KS);
;   float* s_relb = (float*)(smem + 8 * 32 * KS);
;   float* s_gq = s_relb + 512;
;   unsigned char* s_btab = (unsigned char*)(s_gq + 256);
;   s_relb[tid] = p.relb[tid] * LOG2E;
;   if (tid < 256) { s_gq[tid] = p.b_qn[tid]; s_btab[tid] = (unsigned char)t5_bucket(tid - 128); }
;   __syncthreads();
;   for (int row = blockIdx.x * 8 + w; row < M; row += gridDim.x * 8) {
;     const int b = row / T, t = row % T;
;     const int c = t < 16 ? 0 : 1 + ((t - 16) >> 6);
;     const int nvis = 16 + 64 * c;
;     const int nsel = nvis < 256 ? nvis : 256;
;     const int ntile = (nsel + 31) >> 5;
;     const bool use_sel = nvis > 256;
;     int h2 = h;
;     asm volatile("" : "+v"(h2));
;     const float rsq = rsqrtf((ssq[(size_t)row * 32 + 2 * h2] + ssq[(size_t)row * 32 + 2 * h2 + 1]) * (1.f / 256.f) + 1e-6f) * (0.0625f * LOG2E);
;     bf16x8 qf[8];
;     u16* qrowp = qabs + (size_t)row * 4096 + h2 * 256;
; #pragma unroll
;     for (int s = 0; s < 8; ++s) {
;       u32x4 raw = *(const u32x4*)(qrowp + 32 * s + 8 * g);
;       f32x4 g0 = *(const f32x4*)(s_gq + 32 * s + 8 * g), g1 = *(const f32x4*)(s_gq + 32 * s + 8 * g + 4);
;       qf[s] = mk8(pack2(bflo(raw[0]) * rsq * g0[0], bfhi(raw[0]) * rsq * g0[1]), pack2(bflo(raw[1]) * rsq * g0[2], bfhi(raw[1]) * rsq * g0[3]),
;                   pack2(bflo(raw[2]) * rsq * g1[0], bfhi(raw[2]) * rsq * g1[1]), pack2(bflo(raw[3]) * rsq * g1[2], bfhi(raw[3]) * rsq * g1[3]));
;     }
;     f32x4 O[16];
; #pragma unroll
;     for (int rb = 0; rb < 16; ++rb) O[rb] = (f32x4){0.f, 0.f, 0.f, 0.f};
.LBB0_906:
	s_or_b64 exec, exec, s[0:1]
	s_ashr_i32 s0, s2, 6
	v_readlane_b32 s1, v252, 22
	s_add_i32 s6, s0, s1
	s_cmpk_gt_i32 s6, 0x407f
	s_waitcnt lgkmcnt(0)
	s_barrier
	s_cbranch_scc1 .LBB0_918
	v_bfe_u32 v1, v0, 4, 2
	v_mov_b32_e32 v4, 0x22800
	v_and_b32_e32 v145, 31, v0
	v_readlane_b32 s4, v254, 48
	v_and_b32_e32 v143, 15, v0
	v_bfe_u32 v3, v0, 2, 2
	s_mulk_i32 s0, 0x4400
	v_lshlrev_b32_e32 v2, 3, v1
	v_lshl_or_b32 v144, v1, 5, v4
	v_lshlrev_b32_e32 v4, 4, v145
	v_mov_b32_e32 v5, v165
	v_readlane_b32 s5, v254, 49
	v_lshrrev_b32_e32 v6, 3, v0
	v_and_b32_e32 v147, 48, v0
	v_lshlrev_b32_e32 v132, 2, v1
	v_mov_b32_e32 v1, 0x22000
	v_lshl_add_u64 v[130:131], s[4:5], 0, v[4:5]
	v_or_b32_e32 v4, s0, v4
	v_and_b32_e32 v146, 4, v6
	v_or_b32_e32 v6, s0, v147
	v_lshl_or_b32 v148, v143, 2, v1
	v_or_b32_e32 v1, v132, v3
	v_mov_b32_e32 v3, s0
	s_movk_i32 s0, 0x220
	v_and_b32_e32 v142, 63, v0
	v_bfe_u32 v5, v0, 5, 1
	v_mad_u32_u24 v1, v1, s0, v3
	v_lshlrev_b32_e32 v0, 3, v0
	v_and_or_b32 v149, v0, 24, v1
	v_or_b32_e32 v0, 12, v5
	v_lshlrev_b32_e32 v164, 2, v142
	v_mul_u32_u24_e32 v1, 0x220, v5
	v_mul_u32_u24_e32 v3, 0x220, v143
	v_or_b32_e32 v133, 1, v132
	v_or_b32_e32 v135, 3, v132
	v_or_b32_e32 v134, 2, v132
	v_or_b32_e32 v137, 17, v132
	v_or_b32_e32 v136, 16, v132
	v_or_b32_e32 v139, 19, v132
	v_or_b32_e32 v138, 18, v132
	v_lshlrev_b32_e32 v205, 2, v0
	v_mul_u32_u24_e32 v0, 0x220, v0
	v_lshlrev_b32_e32 v5, 2, v5
	v_lshl_add_u64 v[128:129], s[26:27], 0, v[164:165]
	v_xor_b32_e32 v150, 64, v164
	v_xor_b32_e32 v151, 0x80, v164
	v_or_b32_e32 v152, 64, v142
	v_or_b32_e32 v153, 0x80, v142
	v_or_b32_e32 v154, 0xc0, v142
	v_or_b32_e32 v155, 8, v146
	v_or_b32_e32 v156, 16, v146
	v_or_b32_e32 v157, 24, v146
	v_or_b32_e32 v158, 32, v146
	v_or_b32_e32 v159, 40, v146
	v_or_b32_e32 v160, 0x58, v146
	v_or_b32_e32 v161, 0x60, v146
	v_or_b32_e32 v162, 0x68, v146
	v_or_b32_e32 v163, 0x70, v146
	v_or_b32_e32 v166, 0x78, v146
	v_lshlrev_b32_e32 v167, 2, v133
	v_lshlrev_b32_e32 v168, 2, v134
	v_lshlrev_b32_e32 v169, 2, v135
	v_lshlrev_b32_e32 v170, 2, v136
	v_lshlrev_b32_e32 v171, 2, v137
	v_lshlrev_b32_e32 v172, 2, v138
	v_lshlrev_b32_e32 v173, 2, v139
	v_add_u32_e32 v174, 0x2200, v149
	v_add_u32_e32 v175, 32, v149
	v_add_u32_e32 v176, 0x2220, v149
	v_add_u32_e32 v177, 64, v149
	v_add_u32_e32 v178, 0x2240, v149
	v_add_u32_e32 v179, 0x60, v149
	v_add_u32_e32 v180, 0x2260, v149
	v_add_u32_e32 v181, 0x80, v149
	v_add_u32_e32 v182, 0x2280, v149
	v_add_u32_e32 v183, 0xa0, v149
	v_add_u32_e32 v184, 0x22a0, v149
	v_add_u32_e32 v185, 0xc0, v149
	v_add_u32_e32 v186, 0x22c0, v149
	v_add_u32_e32 v187, 0xe0, v149
	v_add_u32_e32 v188, 0x22e0, v149
	v_add_u32_e32 v189, 0x100, v149
	v_add_u32_e32 v190, 0x2300, v149
	v_add_u32_e32 v191, 0x120, v149
	v_add_u32_e32 v192, 0x2320, v149
	v_add_u32_e32 v193, 0x140, v149
	v_add_u32_e32 v194, 0x2340, v149
	v_add_u32_e32 v195, 0x160, v149
	v_add_u32_e32 v196, 0x2360, v149
	v_add_u32_e32 v197, 0x180, v149
	v_add_u32_e32 v198, 0x2380, v149
	v_add_u32_e32 v199, 0x1a0, v149
	v_add_u32_e32 v200, 0x23a0, v149
	v_add_u32_e32 v201, 0x1c0, v149
	v_add_u32_e32 v202, 0x23c0, v149
	v_add_u32_e32 v203, 0x1e0, v149
	v_add_u32_e32 v204, 0x23e0, v149
	v_or_b32_e32 v206, 8, v205
	v_add_u32_e32 v207, 16, v205
	v_add_u32_e32 v208, 24, v205
	v_add_u32_e32 v209, 32, v205
	v_or_b32_e32 v221, 0x58, v5
	v_or_b32_e32 v222, 0x60, v5
	v_or_b32_e32 v223, 0x68, v5
	v_or_b32_e32 v224, 0x70, v5
	v_or_b32_e32 v225, 0x78, v5
	v_lshlrev_b32_e32 v140, 1, v2
	v_add_u32_e32 v226, v6, v3
	v_add_u32_e32 v227, v4, v0
	v_lshlrev_b32_e32 v164, 1, v132
	v_add_u32_e32 v228, v4, v1
	v_readfirstlane_b32 vcc_lo, v210
	s_nop 1
	s_cmp_lt_u32 vcc_lo, 0x100
	s_cbranch_scc1 .Lsp_prio_skip
	s_setprio 1
.Lsp_prio_skip:
	s_branch .LBB0_910
.LBB0_908:
	v_mov_b32_e32 v99, 0
	v_mov_b32_e32 v98, v99
	v_mov_b32_e32 v97, v99
	v_mov_b32_e32 v96, v99
	v_mov_b32_e32 v95, v99
	v_mov_b32_e32 v94, v99
	v_mov_b32_e32 v93, v99
	v_mov_b32_e32 v92, v99
	v_mov_b32_e32 v91, v99
	v_mov_b32_e32 v90, v99
	v_mov_b32_e32 v89, v99
	v_mov_b32_e32 v88, v99
	s_waitcnt lgkmcnt(14)
	v_mov_b32_e32 v87, v99
	v_mov_b32_e32 v86, v99
	v_mov_b32_e32 v85, v99
	v_mov_b32_e32 v84, v99
	v_mov_b32_e32 v83, v99
	v_mov_b32_e32 v82, v99
	v_mov_b32_e32 v81, v99
	v_mov_b32_e32 v80, v99
	v_mov_b32_e32 v79, v99
	v_mov_b32_e32 v78, v99
	v_mov_b32_e32 v77, v99
	v_mov_b32_e32 v76, v99
	v_mov_b32_e32 v75, v99
	v_mov_b32_e32 v74, v99
	v_mov_b32_e32 v73, v99
	v_mov_b32_e32 v72, v99
	v_mov_b32_e32 v71, v99
	v_mov_b32_e32 v70, v99
	v_mov_b32_e32 v69, v99
	v_mov_b32_e32 v68, v99
	v_mov_b32_e32 v67, v99
	v_mov_b32_e32 v66, v99
	v_mov_b32_e32 v65, v99
	v_mov_b32_e32 v64, v99
	v_mov_b32_e32 v63, v99
	v_mov_b32_e32 v62, v99
	v_mov_b32_e32 v61, v99
	v_mov_b32_e32 v60, v99
	v_mov_b32_e32 v59, v99
	v_mov_b32_e32 v58, v99
	v_mov_b32_e32 v57, v99
	v_mov_b32_e32 v56, v99
	v_mov_b32_e32 v55, v99
	v_mov_b32_e32 v54, v99
	v_mov_b32_e32 v53, v99
	v_mov_b32_e32 v52, v99
	v_mov_b32_e32 v51, v99
	v_mov_b32_e32 v50, v99
	v_mov_b32_e32 v49, v99
	v_mov_b32_e32 v48, v99
	v_mov_b32_e32 v47, v99
	v_mov_b32_e32 v46, v99
	v_mov_b32_e32 v45, v99
	v_mov_b32_e32 v44, v99
	v_mov_b32_e32 v43, v99
	v_mov_b32_e32 v42, v99
	v_mov_b32_e32 v41, v99
	v_mov_b32_e32 v40, v99
	v_mov_b32_e32 v39, v99
	v_mov_b32_e32 v38, v99
	v_mov_b32_e32 v37, v99
	v_mov_b32_e32 v36, v99
	v_mov_b32_e32 v233, v99
